# even_c: blocks >= 256 run attention first and the G2 scan afterwards, so on each CU one block scans (memory-bound) while its partner runs attention (matrix-bound)
# speedup vs baseline: 1.0242x; 1.0242x over previous
; DI unsigned xb_add(unsigned* p, unsigned v) { return __hip_atomic_fetch_add(p, v, __ATOMIC_RELAXED, __HIP_MEMORY_SCOPE_AGENT); }
; DI unsigned xb_xcc_id() { return (unsigned)__builtin_amdgcn_s_getreg((3 << 11) | 20) & 0xFu; }
; DI XcdBarrier xcd_barrier_post(unsigned* bar, volatile unsigned* st) {
;   XcdBarrier b; b.bar = bar; b.x = xb_xcc_id(); b.st = st;
;   if (threadIdx.x == 0) (void)xb_add(&bar[XB_XCNT(b.x)], 1u);
;   return b;
; }
; __global__ void __launch_bounds__(NT, 2) fwd_kernel(Params p) {
;   cg::grid_group grid = cg::this_grid();
;   __shared__ __attribute__((aligned(16))) bf16 lds[GEMM_LDS_BF16 + 256];
;   float* sm = (float*)lds;
;   unsigned char* ws = p.ws;
;   Ctx c{p, sm};
;   __shared__ unsigned bar_st[2];
;   if (threadIdx.x == 0) { bar_st[0] = 0u; bar_st[1] = 0u; }
;   __syncthreads();
;   (void)xcd_barrier_post((unsigned*)(ws + WS_BAR), bar_st);
_Z10fwd_kernel6Params:
	s_load_dwordx2 s[88:89], s[0:1], 0xb0
	s_load_dwordx4 s[4:7], s[0:1], 0xa0
	s_mov_b32 s38, s2
	s_add_u32 s2, s0, 0xb8
	s_addc_u32 s3, s1, 0
	v_and_b32_e32 v172, 0x3ff, v0
	v_writelane_b32 v255, 1, 1
	v_writelane_b32 v255, 0, 4
	s_waitcnt lgkmcnt(0)
	v_writelane_b32 v252, s4, 0
	s_nop 1
	v_writelane_b32 v252, s5, 1
	v_writelane_b32 v252, s6, 2
	v_writelane_b32 v252, s7, 3
	s_load_dwordx8 s[4:11], s[0:1], 0x80
	s_waitcnt lgkmcnt(0)
	v_writelane_b32 v252, s4, 4
	s_nop 1
	v_writelane_b32 v252, s5, 5
	v_writelane_b32 v252, s6, 6
	v_writelane_b32 v252, s7, 7
	v_writelane_b32 v252, s8, 8
	v_writelane_b32 v252, s9, 9
	v_writelane_b32 v252, s10, 10
	v_writelane_b32 v252, s11, 11
	v_writelane_b32 v252, s2, 12
	v_cmp_eq_u32_e64 s[4:5], 0, v172
	s_nop 0
	v_writelane_b32 v252, s3, 13
	s_mov_b64 s[2:3], exec
	v_writelane_b32 v252, s4, 14
	s_nop 1
	v_writelane_b32 v252, s5, 15
	s_and_b64 s[4:5], s[2:3], s[4:5]
	s_mov_b64 exec, s[4:5]
	v_mov_b32_e32 v2, 0
	v_mov_b32_e32 v3, v2
	v_mov_b32_e32 v1, 0x12200
	ds_write_b64 v1, v[2:3]
	s_or_b64 exec, exec, s[2:3]
	s_load_dwordx2 s[40:41], s[0:1], 0xb8
	s_load_dword s23, s[0:1], 0xc0
	s_waitcnt lgkmcnt(0)
	s_barrier
	s_getreg_b32 s6, hwreg(HW_REG_XCC_ID, 0, 4)
	s_mov_b64 s[2:3], exec
	v_readlane_b32 s4, v252, 14
	v_readlane_b32 s5, v252, 15
	s_and_b64 s[4:5], s[2:3], s[4:5]
	s_mov_b64 exec, s[4:5]
	s_cbranch_execz .LBB0_5
	s_mov_b64 s[4:5], exec
	v_mbcnt_lo_u32_b32 v1, s4, 0
	v_mbcnt_hi_u32_b32 v1, s5, v1
	v_cmp_eq_u32_e32 vcc, 0, v1
	s_and_b64 s[8:9], exec, vcc
	s_mov_b64 exec, s[8:9]
	s_cbranch_execz .LBB0_5
	s_lshl_b32 s6, s6, 8
	s_and_b32 s6, s6, 0xf00
	s_bcnt1_i32_b64 s4, s[4:5]
	v_mov_b32_e32 v1, s6
	v_mov_b32_e32 v2, s4
	global_atomic_add v1, v2, s[88:89] offset:1024

; DI void phase_even_c(const Ctx& c, int l, bf16* lds) {
;   gla_g2(c);
;   xcd_items(512, [&](int it) { attn_item(c, it, lds); });
; }
.Lg2_entry:
	v_readlane_b32 s2, v252, 32
	v_readlane_b32 s3, v255, 4
	s_cmp_ge_u32 s2, 0x10000
	s_cbranch_scc0 .Lg2_go
	s_cmp_eq_u32 s3, 2
	s_cbranch_scc1 .Lg2_go
	s_mov_b32 s3, 1
	s_nop 0
	v_writelane_b32 v255, s3, 4
	s_branch .LBB0_799

;   DI bf16* G() const { return (bf16*)(p.ws + WS_G); }
; template <class F>
; DI void xcd_items(int total, const F& f) {
;   const int G = gridDim.x;
;   if ((G & 7) == 0 && (total & 7) == 0) {
;     const int x = blockIdx.x & 7, j = blockIdx.x >> 3, per = total >> 3, gl = G >> 3;
;     for (int q = j; q < per; q += gl) f(x * per + q);
; DI void phase_even_c(const Ctx& c, int l, bf16* lds) {
;   gla_g2(c);
;   xcd_items(512, [&](int it) { attn_item(c, it, lds); });
; }
.LBB0_799:
	s_or_b64 exec, exec, s[0:1]
	v_readlane_b32 s3, v255, 4
	s_cmp_eq_u32 s3, 2
	s_cbranch_scc0 .Lg2_cont
	s_mov_b32 s3, 0
	s_nop 0
	v_writelane_b32 v255, s3, 4
	s_branch .Lg2_sync
.Lg2_cont:
	v_readlane_b32 s2, v252, 57
	v_readlane_b32 s3, v252, 58
	s_mov_b64 s[0:1], -1
	s_and_b64 vcc, exec, s[2:3]
	s_cbranch_vccz .LBB0_802
	v_readlane_b32 s0, v253, 33
	v_readlane_b32 s1, v253, 34
	s_andn2_b64 vcc, exec, s[0:1]
	v_readlane_b32 s0, v252, 35
	s_mov_b32 s6, s0
	v_readlane_b32 s1, v252, 36
	s_cbranch_vccz .LBB0_808

; DI void phase_even_c(const Ctx& c, int l, bf16* lds) {
;   gla_g2(c);
;   xcd_items(512, [&](int it) { attn_item(c, it, lds); });
; }
.LBB0_804:
	v_readlane_b32 s3, v255, 4
	s_cmp_eq_u32 s3, 1
	s_cbranch_scc0 .Lg2_sync
	s_mov_b32 s3, 2
	s_nop 0
	v_writelane_b32 v255, s3, 4
	s_mov_b64 s[0:1], exec
	s_branch .Lg2_entry
